# MLA softmax: drop zero-add, fuse l update into one fma, V tile address computed once per tile
# baseline (speedup 1.0000x reference)
; #define MFMA32(a, b, c) __builtin_amdgcn_mfma_f32_32x32x16_bf16((a), (b), (c), 0, 0, 0)
; DI void mla_attention(const int wave_s, const u16* __restrict__ QC, const u16* __restrict__ KF, const u16* __restrict__ Vt, u16* __restrict__ O, char* smem) {
;     ...
;       const u16* kst = Ks + (jt & 1) * 64 * MK_RS;
;       const u16* vst = Vs + (jt & 1) * 64 * MV_RS;
; #pragma unroll
;       for (int half = 0; half < 2; ++half) {
;         const int ks = jt * 64 + half * 32;
;         if (ks <= q0) {
;           const u16* kp = kst + (half * 32 + r) * MK_RS + 8 * h;
;           f32x16 st = zero16();
; #pragma unroll
;           for (int s = 0; s < 6; ++s) {
;             const bf16x8 kf = *(const bf16x8*)(kp + 16 * s);
;             st = MFMA32(kf, qf[s], st);
;           }
;           if (ks == q0) {
; #pragma unroll
;             for (int i = 0; i < 16; ++i)
;               if (crow(i, h) > r) st[i] = -1e30f;
;           }
;           float mx = fmaxf(fmaxf(st[0], st[1]), fmaxf(st[2], st[3]));
; #pragma unroll
;           for (int i = 4; i < 16; i += 4) mx = fmaxf(mx, fmaxf(fmaxf(st[i], st[i + 1]), fmaxf(st[i + 2], st[i + 3])));
;           mx = xhalf_max(mx);
;           const float mn = fmaxf(m, mx);
;           const float alpha = __builtin_amdgcn_exp2f(m - mn);
;           float ps = 0.f;
; #pragma unroll
;           for (int i = 0; i < 16; ++i) {
;             st[i] = __builtin_amdgcn_exp2f(st[i] - mn);
;             ps += st[i];
;           }
;           ps = xhalf_sum(ps);
;           l = l * alpha + ps;
;           m = mn;
;           if (__builtin_amdgcn_ballot_w64(alpha != 1.f) != 0ull) {
; #pragma unroll
;             for (int i = 0; i < 16; ++i) { o0[i] *= alpha; o1[i] *= alpha; }
;           }
;           bf16x8 pf[2];
; #pragma unroll
;           for (int s2 = 0; s2 < 2; ++s2) {
;             uint4 u;
;             u.x = pack2(st[8 * s2 + 0], st[8 * s2 + 1]);
;             u.y = pack2(st[8 * s2 + 2], st[8 * s2 + 3]);
;             u.z = pack2(st[8 * s2 + 4], st[8 * s2 + 5]);
;             u.w = pack2(st[8 * s2 + 6], st[8 * s2 + 7]);
;             pf[s2] = __builtin_bit_cast(bf16x8, u);
;           }
;           const u16* vp = vst + r * MV_RS + half * 32 + 4 * h;
; #pragma unroll
;           for (int s2 = 0; s2 < 2; ++s2) {
;             uint4 u0, u1;
;             const uint2 a0 = *(const uint2*)(vp + 16 * s2), a1 = *(const uint2*)(vp + 16 * s2 + 8);
.LBB0_2395:
	s_and_b32 s42, s94, 64
	s_mul_i32 s43, s42, 0xd0
	v_add_u32_e32 v0, s43, v114
	s_mulk_i32 s42, 0x88
	v_add_u32_e32 v209, s42, v115
	v_add_u32_e32 v208, 0x6800, v209
	v_add_u32_e32 v209, 0x7800, v209
	s_cmp_gt_i32 s94, s93
	v_add_u32_e32 v120, v0, v116
	s_cbranch_scc1 .LBB0_2402
	ds_read_b128 v[34:37], v120
	ds_read_b128 v[122:125], v120 offset:32
	ds_read_b128 v[176:179], v120 offset:64
	ds_read_b128 v[180:183], v120 offset:96
	ds_read_b128 v[184:187], v120 offset:128
	ds_read_b128 v[188:191], v120 offset:160
	ds_read2_b64 v[192:195], v208 offset1:2
	ds_read2_b64 v[196:199], v209 offset0:32 offset1:34
	ds_read2_b64 v[200:203], v208 offset0:4 offset1:6
	ds_read2_b64 v[204:207], v209 offset0:36 offset1:38
	s_cmp_lg_u32 s93, s94
	s_waitcnt lgkmcnt(8)
	v_mfma_f32_32x32x16_bf16 v[34:49], v[34:37], v[50:53], 0
	v_mfma_f32_32x32x16_bf16 v[34:49], v[122:125], v[54:57], v[34:49]
	s_waitcnt lgkmcnt(7)
	v_mfma_f32_32x32x16_bf16 v[34:49], v[176:179], v[58:61], v[34:49]
	s_waitcnt lgkmcnt(6)
	v_mfma_f32_32x32x16_bf16 v[34:49], v[180:183], v[62:65], v[34:49]
	s_waitcnt lgkmcnt(5)
	v_mfma_f32_32x32x16_bf16 v[34:49], v[184:187], v[66:69], v[34:49]
	s_waitcnt lgkmcnt(4)
	v_mfma_f32_32x32x16_bf16 v[34:49], v[188:191], v[70:73], v[34:49]
	s_cbranch_scc1 .LBB0_2398
	s_nop 10
	v_cndmask_b32_e64 v0, v34, v245, s[6:7]
	v_cndmask_b32_e64 v35, v245, v35, s[8:9]
	v_cndmask_b32_e64 v34, v0, v34, s[8:9]
	v_cndmask_b32_e64 v36, v36, v245, s[10:11]
	v_cndmask_b32_e64 v37, v37, v245, s[12:13]
	v_cndmask_b32_e64 v38, v38, v245, s[14:15]
	v_cndmask_b32_e64 v39, v39, v245, s[16:17]
	v_cndmask_b32_e64 v40, v40, v245, s[18:19]
	v_cndmask_b32_e64 v41, v41, v245, s[20:21]
	v_cndmask_b32_e64 v42, v42, v245, s[22:23]
	v_cndmask_b32_e64 v43, v43, v245, s[24:25]
	v_cndmask_b32_e64 v44, v44, v245, s[26:27]
	v_cndmask_b32_e64 v45, v45, v245, s[28:29]
	v_cndmask_b32_e64 v46, v46, v245, s[30:31]
	v_cndmask_b32_e64 v47, v47, v245, s[34:35]
	v_cndmask_b32_e64 v48, v48, v245, s[36:37]
	v_cndmask_b32_e64 v49, v49, v245, s[38:39]
.LBB0_2398:
	s_nop 10
	v_max3_f32 v0, v34, v35, v36
	v_max3_f32 v121, v37, v38, v39
	v_max3_f32 v122, v40, v41, v42
	v_max3_f32 v123, v43, v44, v45
	v_max3_f32 v0, v0, v46, v47
	v_max3_f32 v121, v121, v48, v49
	v_max3_f32 v0, v0, v121, v122
	v_max_f32_e32 v0, v0, v123
	v_mov_b32_e32 v121, v0
	s_nop 1
	v_permlane32_swap_b32_e32 v0, v121
	v_max3_f32 v121, v119, v0, v121
	v_sub_f32_e32 v34, v34, v121
	v_sub_f32_e32 v0, v119, v121
	v_exp_f32_e32 v119, v34
	v_sub_f32_e32 v34, v35, v121
	v_exp_f32_e32 v122, v34
	v_sub_f32_e32 v34, v36, v121
	v_exp_f32_e32 v123, v34
	v_sub_f32_e32 v34, v37, v121
	v_exp_f32_e32 v124, v34
	v_sub_f32_e32 v35, v38, v121
	v_exp_f32_e32 v125, v35
	v_sub_f32_e32 v35, v39, v121
	v_add_f32_e32 v34, v122, v119
	v_exp_f32_e32 v126, v35
	v_sub_f32_e32 v35, v40, v121
	v_add_f32_e32 v34, v123, v34
	v_exp_f32_e32 v127, v35
	v_sub_f32_e32 v35, v41, v121
	v_add_f32_e32 v34, v124, v34
	v_exp_f32_e32 v128, v35
	v_add_f32_e32 v34, v125, v34
	v_add_f32_e32 v34, v126, v34
	v_add_f32_e32 v34, v127, v34
	v_add_f32_e32 v37, v128, v34
	v_sub_f32_e32 v34, v42, v121
	v_exp_f32_e32 v34, v34
	v_sub_f32_e32 v35, v43, v121
	v_exp_f32_e32 v35, v35
	v_sub_f32_e32 v36, v44, v121
	v_exp_f32_e32 v36, v36
	v_sub_f32_e32 v38, v45, v121
	v_exp_f32_e32 v38, v38
	v_sub_f32_e32 v39, v46, v121
	v_add_f32_e32 v37, v34, v37
	v_exp_f32_e32 v40, v39
	v_sub_f32_e32 v39, v47, v121
	v_add_f32_e32 v37, v35, v37
	v_exp_f32_e32 v41, v39
	v_sub_f32_e32 v39, v48, v121
	v_add_f32_e32 v37, v36, v37
	v_exp_f32_e32 v42, v39
	v_sub_f32_e32 v39, v49, v121
	v_add_f32_e32 v37, v38, v37
	v_exp_f32_e32 v43, v39
	v_add_f32_e32 v37, v40, v37
	v_add_f32_e32 v37, v41, v37
	v_exp_f32_e32 v0, v0
	v_add_f32_e32 v37, v42, v37
	v_add_f32_e32 v37, v43, v37
	v_mov_b32_e32 v39, v37
	s_nop 1
	v_permlane32_swap_b32_e32 v37, v39
	v_cmp_neq_f32_e32 vcc, 1.0, v0
	s_cbranch_vccz .LBB0_2400
	v_pk_mul_f32 v[32:33], v[32:33], v[0:1] op_sel_hi:[1,0]
	v_pk_mul_f32 v[30:31], v[30:31], v[0:1] op_sel_hi:[1,0]
	v_pk_mul_f32 v[28:29], v[28:29], v[0:1] op_sel_hi:[1,0]
	v_pk_mul_f32 v[26:27], v[26:27], v[0:1] op_sel_hi:[1,0]
	v_pk_mul_f32 v[24:25], v[24:25], v[0:1] op_sel_hi:[1,0]
	v_pk_mul_f32 v[22:23], v[22:23], v[0:1] op_sel_hi:[1,0]
	v_pk_mul_f32 v[20:21], v[20:21], v[0:1] op_sel_hi:[1,0]
	v_pk_mul_f32 v[18:19], v[18:19], v[0:1] op_sel_hi:[1,0]
	v_pk_mul_f32 v[16:17], v[16:17], v[0:1] op_sel_hi:[1,0]
	v_pk_mul_f32 v[14:15], v[14:15], v[0:1] op_sel_hi:[1,0]
	v_pk_mul_f32 v[12:13], v[12:13], v[0:1] op_sel_hi:[1,0]
	v_pk_mul_f32 v[10:11], v[10:11], v[0:1] op_sel_hi:[1,0]
	v_pk_mul_f32 v[8:9], v[8:9], v[0:1] op_sel_hi:[1,0]
	v_pk_mul_f32 v[6:7], v[6:7], v[0:1] op_sel_hi:[1,0]
	v_pk_mul_f32 v[4:5], v[4:5], v[0:1] op_sel_hi:[1,0]
	v_pk_mul_f32 v[2:3], v[2:3], v[0:1] op_sel_hi:[1,0]
.LBB0_2400:
	v_cvt_pk_bf16_f32 v122, v119, v122
	v_cvt_pk_bf16_f32 v123, v123, v124
	v_cvt_pk_bf16_f32 v124, v125, v126
	v_cvt_pk_bf16_f32 v125, v127, v128
	s_nop 0
	s_waitcnt lgkmcnt(0)
	v_mfma_f32_32x32x16_bf16 v[18:33], v[192:195], v[122:125], v[18:33]
	v_mfma_f32_32x32x16_bf16 v[2:17], v[196:199], v[122:125], v[2:17]
	v_cvt_pk_bf16_f32 v124, v40, v41
	v_cvt_pk_bf16_f32 v125, v42, v43
	v_cvt_pk_bf16_f32 v122, v34, v35
	v_cvt_pk_bf16_f32 v123, v36, v38
	v_add_f32_e32 v34, v37, v39
	v_fma_f32 v118, v118, v0, v34
	s_nop 0
	v_mfma_f32_32x32x16_bf16 v[18:33], v[200:203], v[122:125], v[18:33]
	v_mfma_f32_32x32x16_bf16 v[2:17], v[204:207], v[122:125], v[2:17]
	s_cmp_ge_i32 s94, s93
	s_cbranch_scc0 .LBB0_2403

; DI void mla_attention(const int wave_s, const u16* __restrict__ QC, const u16* __restrict__ KF, const u16* __restrict__ Vt, u16* __restrict__ O, char* smem) {
;     ...
;       for (int half = 0; half < 2; ++half) {
;         const int ks = jt * 64 + half * 32;
;         if (ks <= q0) {
;           const u16* kp = kst + (half * 32 + r) * MK_RS + 8 * h;
;           f32x16 st = zero16();
; #pragma unroll
;           for (int s = 0; s < 6; ++s) {
;             const bf16x8 kf = *(const bf16x8*)(kp + 16 * s);
;             st = MFMA32(kf, qf[s], st);
;           }
;           if (ks == q0) {
; #pragma unroll
;             for (int i = 0; i < 16; ++i)
;               if (crow(i, h) > r) st[i] = -1e30f;
;           }
;           float mx = fmaxf(fmaxf(st[0], st[1]), fmaxf(st[2], st[3]));
; #pragma unroll
;           for (int i = 4; i < 16; i += 4) mx = fmaxf(mx, fmaxf(fmaxf(st[i], st[i + 1]), fmaxf(st[i + 2], st[i + 3])));
;           mx = xhalf_max(mx);
;           const float mn = fmaxf(m, mx);
;           const float alpha = __builtin_amdgcn_exp2f(m - mn);
;           float ps = 0.f;
; #pragma unroll
;           for (int i = 0; i < 16; ++i) {
;             st[i] = __builtin_amdgcn_exp2f(st[i] - mn);
;             ps += st[i];
;           }
;           ps = xhalf_sum(ps);
;           l = l * alpha + ps;
;           m = mn;
;           if (__builtin_amdgcn_ballot_w64(alpha != 1.f) != 0ull) {
; #pragma unroll
;             for (int i = 0; i < 16; ++i) { o0[i] *= alpha; o1[i] *= alpha; }
;           }
;           bf16x8 pf[2];
; #pragma unroll
;           for (int s2 = 0; s2 < 2; ++s2) {
;             uint4 u;
;             u.x = pack2(st[8 * s2 + 0], st[8 * s2 + 1]);
;             u.y = pack2(st[8 * s2 + 2], st[8 * s2 + 3]);
;             u.z = pack2(st[8 * s2 + 4], st[8 * s2 + 5]);
;             u.w = pack2(st[8 * s2 + 6], st[8 * s2 + 7]);
;             pf[s2] = __builtin_bit_cast(bf16x8, u);
;           }
;           const u16* vp = vst + r * MV_RS + half * 32 + 4 * h;
; #pragma unroll
;           for (int s2 = 0; s2 < 2; ++s2) {
;             uint4 u0, u1;
;             const uint2 a0 = *(const uint2*)(vp + 16 * s2), a1 = *(const uint2*)(vp + 16 * s2 + 8);
;             const uint2 b0 = *(const uint2*)(vp + 32 * MV_RS + 16 * s2), b1 = *(const uint2*)(vp + 32 * MV_RS + 16 * s2 + 8);
;             u0.x = a0.x; u0.y = a0.y; u0.z = a1.x; u0.w = a1.y;
.LBB0_2403:
	ds_read_b128 v[34:37], v120 offset:6656
	ds_read_b128 v[122:125], v120 offset:6688
	ds_read_b128 v[176:179], v120 offset:6720
	ds_read_b128 v[180:183], v120 offset:6752
	ds_read_b128 v[184:187], v120 offset:6784
	ds_read_b128 v[188:191], v120 offset:6816
	ds_read2_b64 v[192:195], v208 offset0:8 offset1:10
	ds_read2_b64 v[196:199], v209 offset0:40 offset1:42
	ds_read2_b64 v[200:203], v208 offset0:12 offset1:14
	ds_read2_b64 v[204:207], v209 offset0:44 offset1:46
	s_cmp_lg_u32 s81, s94
	s_waitcnt lgkmcnt(8)
	v_mfma_f32_32x32x16_bf16 v[34:49], v[34:37], v[50:53], 0
	v_mfma_f32_32x32x16_bf16 v[34:49], v[122:125], v[54:57], v[34:49]
	s_waitcnt lgkmcnt(7)
	v_mfma_f32_32x32x16_bf16 v[34:49], v[176:179], v[58:61], v[34:49]
	s_waitcnt lgkmcnt(6)
	v_mfma_f32_32x32x16_bf16 v[34:49], v[180:183], v[62:65], v[34:49]
	s_waitcnt lgkmcnt(5)
	v_mfma_f32_32x32x16_bf16 v[34:49], v[184:187], v[66:69], v[34:49]
	s_waitcnt lgkmcnt(4)
	v_mfma_f32_32x32x16_bf16 v[34:49], v[188:191], v[70:73], v[34:49]
	s_cbranch_scc1 .LBB0_2405
	s_nop 10
	v_cndmask_b32_e64 v0, v34, v245, s[6:7]
	v_cndmask_b32_e64 v35, v245, v35, s[8:9]
	v_cndmask_b32_e64 v34, v0, v34, s[8:9]
	v_cndmask_b32_e64 v36, v36, v245, s[10:11]
	v_cndmask_b32_e64 v37, v37, v245, s[12:13]
	v_cndmask_b32_e64 v38, v38, v245, s[14:15]
	v_cndmask_b32_e64 v39, v39, v245, s[16:17]
	v_cndmask_b32_e64 v40, v40, v245, s[18:19]
	v_cndmask_b32_e64 v41, v41, v245, s[20:21]
	v_cndmask_b32_e64 v42, v42, v245, s[22:23]
	v_cndmask_b32_e64 v43, v43, v245, s[24:25]
	v_cndmask_b32_e64 v44, v44, v245, s[26:27]
	v_cndmask_b32_e64 v45, v45, v245, s[28:29]
	v_cndmask_b32_e64 v46, v46, v245, s[30:31]
	v_cndmask_b32_e64 v47, v47, v245, s[34:35]
	v_cndmask_b32_e64 v48, v48, v245, s[36:37]
	v_cndmask_b32_e64 v49, v49, v245, s[38:39]
.LBB0_2405:
	s_nop 10
	v_max3_f32 v0, v34, v35, v36
	v_max3_f32 v119, v37, v38, v39
	v_max3_f32 v120, v40, v41, v42
	v_max3_f32 v122, v43, v44, v45
	v_max3_f32 v0, v0, v46, v47
	v_max3_f32 v119, v119, v48, v49
	v_max3_f32 v0, v0, v119, v120
	v_max_f32_e32 v0, v0, v122
	v_mov_b32_e32 v119, v0
	s_nop 1
	v_permlane32_swap_b32_e32 v0, v119
	v_max3_f32 v119, v121, v0, v119
	v_sub_f32_e32 v34, v34, v119
	v_exp_f32_e32 v120, v34
	v_sub_f32_e32 v34, v35, v119
	v_sub_f32_e32 v0, v121, v119
	v_exp_f32_e32 v121, v34
	v_sub_f32_e32 v34, v36, v119
	v_exp_f32_e32 v122, v34
	v_sub_f32_e32 v34, v37, v119
	v_exp_f32_e32 v123, v34
	v_sub_f32_e32 v35, v38, v119
	v_exp_f32_e32 v124, v35
	v_sub_f32_e32 v35, v39, v119
	v_add_f32_e32 v34, v121, v120
	v_exp_f32_e32 v125, v35
	v_sub_f32_e32 v35, v40, v119
	v_add_f32_e32 v34, v122, v34
	v_exp_f32_e32 v126, v35
	v_sub_f32_e32 v35, v41, v119
	v_add_f32_e32 v34, v123, v34
	v_exp_f32_e32 v127, v35
	v_add_f32_e32 v34, v124, v34
	v_add_f32_e32 v34, v125, v34
	v_add_f32_e32 v34, v126, v34
	v_add_f32_e32 v37, v127, v34
	v_sub_f32_e32 v34, v42, v119
	v_exp_f32_e32 v34, v34
	v_sub_f32_e32 v35, v43, v119
	v_exp_f32_e32 v35, v35
	v_sub_f32_e32 v36, v44, v119
	v_exp_f32_e32 v36, v36
	v_sub_f32_e32 v38, v45, v119
	v_exp_f32_e32 v38, v38
	v_sub_f32_e32 v39, v46, v119
	v_add_f32_e32 v37, v34, v37
	v_exp_f32_e32 v40, v39
	v_sub_f32_e32 v39, v47, v119
	v_add_f32_e32 v37, v35, v37
	v_exp_f32_e32 v41, v39
	v_sub_f32_e32 v39, v48, v119
	v_add_f32_e32 v37, v36, v37
	v_exp_f32_e32 v42, v39
	v_sub_f32_e32 v39, v49, v119
	v_add_f32_e32 v37, v38, v37
	v_exp_f32_e32 v43, v39
	v_add_f32_e32 v37, v40, v37
	v_add_f32_e32 v37, v41, v37
	v_exp_f32_e32 v0, v0
	v_add_f32_e32 v37, v42, v37
	v_add_f32_e32 v37, v43, v37
	v_mov_b32_e32 v39, v37
	s_nop 1
	v_permlane32_swap_b32_e32 v37, v39
	v_cmp_neq_f32_e32 vcc, 1.0, v0
	s_cbranch_vccz .LBB0_2407
	v_pk_mul_f32 v[32:33], v[32:33], v[0:1] op_sel_hi:[1,0]
	v_pk_mul_f32 v[30:31], v[30:31], v[0:1] op_sel_hi:[1,0]
	v_pk_mul_f32 v[28:29], v[28:29], v[0:1] op_sel_hi:[1,0]
	v_pk_mul_f32 v[26:27], v[26:27], v[0:1] op_sel_hi:[1,0]
	v_pk_mul_f32 v[24:25], v[24:25], v[0:1] op_sel_hi:[1,0]
	v_pk_mul_f32 v[22:23], v[22:23], v[0:1] op_sel_hi:[1,0]
	v_pk_mul_f32 v[20:21], v[20:21], v[0:1] op_sel_hi:[1,0]
	v_pk_mul_f32 v[18:19], v[18:19], v[0:1] op_sel_hi:[1,0]
	v_pk_mul_f32 v[16:17], v[16:17], v[0:1] op_sel_hi:[1,0]
	v_pk_mul_f32 v[14:15], v[14:15], v[0:1] op_sel_hi:[1,0]
	v_pk_mul_f32 v[12:13], v[12:13], v[0:1] op_sel_hi:[1,0]
	v_pk_mul_f32 v[10:11], v[10:11], v[0:1] op_sel_hi:[1,0]
	v_pk_mul_f32 v[8:9], v[8:9], v[0:1] op_sel_hi:[1,0]
	v_pk_mul_f32 v[6:7], v[6:7], v[0:1] op_sel_hi:[1,0]
	v_pk_mul_f32 v[4:5], v[4:5], v[0:1] op_sel_hi:[1,0]
	v_pk_mul_f32 v[2:3], v[2:3], v[0:1] op_sel_hi:[1,0]
.LBB0_2407:
	v_cvt_pk_bf16_f32 v120, v120, v121
	v_cvt_pk_bf16_f32 v121, v122, v123
	v_cvt_pk_bf16_f32 v122, v124, v125
	v_cvt_pk_bf16_f32 v123, v126, v127
	s_nop 0
	s_waitcnt lgkmcnt(0)
	v_mfma_f32_32x32x16_bf16 v[18:33], v[192:195], v[120:123], v[18:33]
	v_mfma_f32_32x32x16_bf16 v[2:17], v[196:199], v[120:123], v[2:17]
	v_cvt_pk_bf16_f32 v122, v40, v41
	v_cvt_pk_bf16_f32 v123, v42, v43
	v_cvt_pk_bf16_f32 v120, v34, v35
	v_cvt_pk_bf16_f32 v121, v36, v38
	v_add_f32_e32 v34, v37, v39
	v_fma_f32 v118, v118, v0, v34
	s_nop 0
	v_mfma_f32_32x32x16_bf16 v[18:33], v[200:203], v[120:123], v[18:33]
	v_mfma_f32_32x32x16_bf16 v[2:17], v[204:207], v[120:123], v[2:17]
	s_andn2_b64 vcc, exec, s[74:75]
	s_mov_b64 s[42:43], -1
	s_cbranch_vccnz .LBB0_2409
